# P10b GEMM epilogue: the 16 per-chunk re-reads of the previous GEMM's output requested together at the top of the epilogue instead of one round trip per chunk
# baseline (speedup 1.0000x reference)
.LBB0_1094:
	v_lshl_add_u32 v144, s0, 8, v148
	s_lshl_b32 s0, s20, 8
	v_ashrrev_i32_e32 v145, 31, v144
	s_and_b32 s0, s0, 0x300
	v_or_b32_e32 v162, s0, v150
	v_lshlrev_b64 v[146:147], 10, v[144:145]
	s_cmp_lt_u32 s20, 4
	s_cselect_b64 s[44:45], -1, 0
	s_cmp_gt_u32 s20, 3
	v_or_b32_e32 v146, v146, v162
	v_mov_b32_e32 v240, v146
	v_mov_b32_e32 v241, v147
	v_lshl_add_u64 v[242:243], v[240:241], 1, s[2:3]
	global_load_dwordx4 v[176:179], v[242:243], off
	v_or_b32_e32 v240, 0x80, v240
	v_lshl_add_u64 v[242:243], v[240:241], 1, s[2:3]
	global_load_dwordx4 v[180:183], v[242:243], off
	v_or_b32_e32 v240, 16, v144
	v_ashrrev_i32_e32 v241, 31, v240
	v_lshlrev_b64 v[240:241], 10, v[240:241]
	v_or_b32_e32 v240, v240, v162
	v_lshl_add_u64 v[242:243], v[240:241], 1, s[2:3]
	global_load_dwordx4 v[184:187], v[242:243], off
	v_or_b32_e32 v240, 0x80, v240
	v_lshl_add_u64 v[242:243], v[240:241], 1, s[2:3]
	global_load_dwordx4 v[188:191], v[242:243], off
	v_or_b32_e32 v240, 32, v144
	v_ashrrev_i32_e32 v241, 31, v240
	v_lshlrev_b64 v[240:241], 10, v[240:241]
	v_or_b32_e32 v240, v240, v162
	v_lshl_add_u64 v[242:243], v[240:241], 1, s[2:3]
	global_load_dwordx4 v[192:195], v[242:243], off
	v_or_b32_e32 v240, 0x80, v240
	v_lshl_add_u64 v[242:243], v[240:241], 1, s[2:3]
	global_load_dwordx4 v[196:199], v[242:243], off
	v_or_b32_e32 v240, 48, v144
	v_ashrrev_i32_e32 v241, 31, v240
	v_lshlrev_b64 v[240:241], 10, v[240:241]
	v_or_b32_e32 v240, v240, v162
	v_lshl_add_u64 v[242:243], v[240:241], 1, s[2:3]
	global_load_dwordx4 v[200:203], v[242:243], off
	v_or_b32_e32 v240, 0x80, v240
	v_lshl_add_u64 v[242:243], v[240:241], 1, s[2:3]
	global_load_dwordx4 v[204:207], v[242:243], off
	v_lshlrev_b64 v[240:241], 10, v[144:145]
	v_or_b32_e32 v240, v240, v162
	v_lshl_add_u64 v[240:241], v[240:241], 0, s[22:23]
	v_lshl_add_u64 v[242:243], v[240:241], 1, s[2:3]
	global_load_dwordx4 v[208:211], v[242:243], off
	v_or_b32_e32 v240, 0x80, v240
	v_lshl_add_u64 v[242:243], v[240:241], 1, s[2:3]
	global_load_dwordx4 v[212:215], v[242:243], off
	v_lshlrev_b64 v[240:241], 10, v[144:145]
	v_or_b32_e32 v240, v240, v162
	v_lshl_add_u64 v[240:241], v[240:241], 0, s[24:25]
	v_lshl_add_u64 v[242:243], v[240:241], 1, s[2:3]
	global_load_dwordx4 v[216:219], v[242:243], off
	v_or_b32_e32 v240, 0x80, v240
	v_lshl_add_u64 v[242:243], v[240:241], 1, s[2:3]
	global_load_dwordx4 v[220:223], v[242:243], off
	v_lshlrev_b64 v[240:241], 10, v[144:145]
	v_or_b32_e32 v240, v240, v162
	v_lshl_add_u64 v[240:241], v[240:241], 0, s[26:27]
	v_lshl_add_u64 v[242:243], v[240:241], 1, s[2:3]
	global_load_dwordx4 v[224:227], v[242:243], off
	v_or_b32_e32 v240, 0x80, v240
	v_lshl_add_u64 v[242:243], v[240:241], 1, s[2:3]
	global_load_dwordx4 v[228:231], v[242:243], off
	v_lshlrev_b64 v[240:241], 10, v[144:145]
	v_or_b32_e32 v240, v240, v162
	v_lshl_add_u64 v[240:241], v[240:241], 0, s[34:35]
	v_lshl_add_u64 v[242:243], v[240:241], 1, s[2:3]
	global_load_dwordx4 v[232:235], v[242:243], off
	v_or_b32_e32 v240, 0x80, v240
	v_lshl_add_u64 v[242:243], v[240:241], 1, s[2:3]
	global_load_dwordx4 v[236:239], v[242:243], off
	s_cbranch_scc1 .LBB0_1096
	v_lshl_add_u64 v[164:165], v[146:147], 1, s[14:15]
	global_load_dwordx4 v[164:167], v[164:165], off
	s_waitcnt vmcnt(0)
	v_lshlrev_b32_e32 v168, 16, v164
	v_and_b32_e32 v169, 0xffff0000, v164
	v_lshlrev_b32_e32 v164, 16, v165
	v_and_b32_e32 v165, 0xffff0000, v165
	v_lshlrev_b32_e32 v172, 16, v166
	v_and_b32_e32 v173, 0xffff0000, v166
	v_lshlrev_b32_e32 v166, 16, v167
	v_and_b32_e32 v167, 0xffff0000, v167
	v_pk_mul_f32 v[124:125], v[124:125], v[168:169]
	v_pk_mul_f32 v[126:127], v[126:127], v[164:165]
	v_pk_mul_f32 v[120:121], v[120:121], v[172:173]
	v_pk_mul_f32 v[122:123], v[122:123], v[166:167]
.LBB0_1096:
	v_lshlrev_b64 v[168:169], 1, v[146:147]
	v_cndmask_b32_e64 v163, 0, 1, s[44:45]
	v_lshl_add_u64 v[168:169], s[10:11], 0, v[168:169]
	v_cmp_ne_u32_e64 s[0:1], 1, v163
	s_andn2_b64 vcc, exec, s[44:45]
	v_or_b32_e32 v146, 0x80, v146
	s_waitcnt vmcnt(0)
	v_pk_mov_b32 v[164:165], v[176:177], v[176:177] op_sel:[0,1] op_sel_hi:[0,1]
	v_pk_mov_b32 v[166:167], v[178:179], v[178:179] op_sel:[0,1] op_sel_hi:[0,1]
	v_lshlrev_b32_e32 v172, 16, v164
	v_and_b32_e32 v173, 0xffff0000, v164
	v_lshlrev_b32_e32 v164, 16, v165
	v_and_b32_e32 v165, 0xffff0000, v165
	v_lshlrev_b32_e32 v174, 16, v166
	v_and_b32_e32 v175, 0xffff0000, v166
	v_lshlrev_b32_e32 v166, 16, v167
	v_and_b32_e32 v167, 0xffff0000, v167
	v_pk_add_f32 v[124:125], v[124:125], v[172:173]
	v_pk_add_f32 v[126:127], v[126:127], v[164:165]
	v_pk_add_f32 v[164:165], v[120:121], v[174:175]
	v_pk_add_f32 v[166:167], v[122:123], v[166:167]
	v_cvt_pk_bf16_f32 v120, v124, v125
	v_cvt_pk_bf16_f32 v121, v126, v127
	v_cvt_pk_bf16_f32 v122, v164, v165
	v_cvt_pk_bf16_f32 v123, v166, v167
	global_store_dwordx4 v[168:169], v[120:123], off
	s_cbranch_vccnz .LBB0_1098
	s_nop 0
	v_lshl_add_u64 v[120:121], v[146:147], 1, s[14:15]
	global_load_dwordx4 v[120:123], v[120:121], off
	s_waitcnt vmcnt(0)
	v_lshlrev_b32_e32 v124, 16, v120
	v_and_b32_e32 v125, 0xffff0000, v120
	v_lshlrev_b32_e32 v120, 16, v121
	v_and_b32_e32 v121, 0xffff0000, v121
	v_lshlrev_b32_e32 v126, 16, v122
	v_and_b32_e32 v127, 0xffff0000, v122
	v_lshlrev_b32_e32 v122, 16, v123
	v_and_b32_e32 v123, 0xffff0000, v123
	v_pk_mul_f32 v[116:117], v[116:117], v[124:125]
	v_pk_mul_f32 v[118:119], v[118:119], v[120:121]
	v_pk_mul_f32 v[112:113], v[112:113], v[126:127]
	v_pk_mul_f32 v[114:115], v[114:115], v[122:123]
.LBB0_1098:
	s_nop 0
	v_lshlrev_b64 v[120:121], 1, v[146:147]
	v_or_b32_e32 v126, 16, v144
	v_ashrrev_i32_e32 v127, 31, v126
	v_lshl_add_u64 v[146:147], s[10:11], 0, v[120:121]
	v_lshlrev_b64 v[120:121], 10, v[126:127]
	s_and_b64 vcc, exec, s[0:1]
	v_or_b32_e32 v120, v120, v162
	v_readlane_b32 s72, v247, 48
	v_readlane_b32 s73, v247, 49
	s_waitcnt vmcnt(0)
	v_pk_mov_b32 v[122:123], v[180:181], v[180:181] op_sel:[0,1] op_sel_hi:[0,1]
	v_pk_mov_b32 v[124:125], v[182:183], v[182:183] op_sel:[0,1] op_sel_hi:[0,1]
	v_lshlrev_b32_e32 v126, 16, v122
	v_and_b32_e32 v127, 0xffff0000, v122
	v_lshlrev_b32_e32 v122, 16, v123
	v_and_b32_e32 v123, 0xffff0000, v123
	v_lshlrev_b32_e32 v164, 16, v124
	v_and_b32_e32 v165, 0xffff0000, v124
	v_lshlrev_b32_e32 v124, 16, v125
	v_and_b32_e32 v125, 0xffff0000, v125
	v_pk_add_f32 v[116:117], v[116:117], v[126:127]
	v_pk_add_f32 v[118:119], v[118:119], v[122:123]
	v_pk_add_f32 v[122:123], v[112:113], v[164:165]
	v_pk_add_f32 v[124:125], v[114:115], v[124:125]
	v_cvt_pk_bf16_f32 v112, v116, v117
	v_cvt_pk_bf16_f32 v113, v118, v119
	v_cvt_pk_bf16_f32 v114, v122, v123
	v_cvt_pk_bf16_f32 v115, v124, v125
	global_store_dwordx4 v[146:147], v[112:115], off
	s_cbranch_vccnz .LBB0_1100
	s_nop 0
	v_lshl_add_u64 v[112:113], v[120:121], 1, s[14:15]
	global_load_dwordx4 v[112:115], v[112:113], off
	s_waitcnt vmcnt(0)
	v_lshlrev_b32_e32 v116, 16, v112
	v_and_b32_e32 v117, 0xffff0000, v112
	v_lshlrev_b32_e32 v112, 16, v113
	v_and_b32_e32 v113, 0xffff0000, v113
	v_lshlrev_b32_e32 v118, 16, v114
	v_and_b32_e32 v119, 0xffff0000, v114
	v_lshlrev_b32_e32 v114, 16, v115
	v_and_b32_e32 v115, 0xffff0000, v115
	v_pk_mul_f32 v[108:109], v[108:109], v[116:117]
	v_pk_mul_f32 v[110:111], v[110:111], v[112:113]
	v_pk_mul_f32 v[104:105], v[104:105], v[118:119]
	v_pk_mul_f32 v[106:107], v[106:107], v[114:115]
.LBB0_1100:
	v_lshlrev_b64 v[116:117], 1, v[120:121]
	s_and_b64 vcc, exec, s[0:1]
	v_lshl_add_u64 v[116:117], s[10:11], 0, v[116:117]
	v_or_b32_e32 v120, 0x80, v120
	s_waitcnt vmcnt(0)
	v_pk_mov_b32 v[112:113], v[184:185], v[184:185] op_sel:[0,1] op_sel_hi:[0,1]
	v_pk_mov_b32 v[114:115], v[186:187], v[186:187] op_sel:[0,1] op_sel_hi:[0,1]
	v_lshlrev_b32_e32 v118, 16, v112
	v_and_b32_e32 v119, 0xffff0000, v112
	v_lshlrev_b32_e32 v112, 16, v113
	v_and_b32_e32 v113, 0xffff0000, v113
	v_lshlrev_b32_e32 v122, 16, v114
	v_and_b32_e32 v123, 0xffff0000, v114
	v_lshlrev_b32_e32 v114, 16, v115
	v_and_b32_e32 v115, 0xffff0000, v115
	v_pk_add_f32 v[108:109], v[108:109], v[118:119]
	v_pk_add_f32 v[110:111], v[110:111], v[112:113]
	v_pk_add_f32 v[112:113], v[104:105], v[122:123]
	v_pk_add_f32 v[114:115], v[106:107], v[114:115]
	v_cvt_pk_bf16_f32 v104, v108, v109
	v_cvt_pk_bf16_f32 v105, v110, v111
	v_cvt_pk_bf16_f32 v106, v112, v113
	v_cvt_pk_bf16_f32 v107, v114, v115
	global_store_dwordx4 v[116:117], v[104:107], off
	s_cbranch_vccnz .LBB0_1102
	s_nop 0
	v_lshl_add_u64 v[104:105], v[120:121], 1, s[14:15]
	global_load_dwordx4 v[104:107], v[104:105], off
	s_waitcnt vmcnt(0)
	v_lshlrev_b32_e32 v108, 16, v104
	v_and_b32_e32 v109, 0xffff0000, v104
	v_lshlrev_b32_e32 v104, 16, v105
	v_and_b32_e32 v105, 0xffff0000, v105
	v_lshlrev_b32_e32 v110, 16, v106
	v_and_b32_e32 v111, 0xffff0000, v106
	v_lshlrev_b32_e32 v106, 16, v107
	v_and_b32_e32 v107, 0xffff0000, v107
	v_pk_mul_f32 v[100:101], v[100:101], v[108:109]
	v_pk_mul_f32 v[102:103], v[102:103], v[104:105]
	v_pk_mul_f32 v[96:97], v[96:97], v[110:111]
	v_pk_mul_f32 v[98:99], v[98:99], v[106:107]
.LBB0_1102:
	s_nop 0
	v_lshlrev_b64 v[104:105], 1, v[120:121]
	v_or_b32_e32 v110, 32, v144
	v_ashrrev_i32_e32 v111, 31, v110
	v_lshl_add_u64 v[112:113], s[10:11], 0, v[104:105]
	v_lshlrev_b64 v[104:105], 10, v[110:111]
	s_and_b64 vcc, exec, s[0:1]
	v_or_b32_e32 v104, v104, v162
	s_waitcnt vmcnt(0)
	v_pk_mov_b32 v[106:107], v[188:189], v[188:189] op_sel:[0,1] op_sel_hi:[0,1]
	v_pk_mov_b32 v[108:109], v[190:191], v[190:191] op_sel:[0,1] op_sel_hi:[0,1]
	v_lshlrev_b32_e32 v110, 16, v106
	v_and_b32_e32 v111, 0xffff0000, v106
	v_lshlrev_b32_e32 v106, 16, v107
	v_and_b32_e32 v107, 0xffff0000, v107
	v_lshlrev_b32_e32 v114, 16, v108
	v_and_b32_e32 v115, 0xffff0000, v108
	v_lshlrev_b32_e32 v108, 16, v109
	v_and_b32_e32 v109, 0xffff0000, v109
	v_pk_add_f32 v[100:101], v[100:101], v[110:111]
	v_pk_add_f32 v[102:103], v[102:103], v[106:107]
	v_pk_add_f32 v[106:107], v[96:97], v[114:115]
	v_pk_add_f32 v[108:109], v[98:99], v[108:109]
	v_cvt_pk_bf16_f32 v96, v100, v101
	v_cvt_pk_bf16_f32 v97, v102, v103
	v_cvt_pk_bf16_f32 v98, v106, v107
	v_cvt_pk_bf16_f32 v99, v108, v109
	global_store_dwordx4 v[112:113], v[96:99], off
	s_cbranch_vccnz .LBB0_1104
	s_nop 0
	v_lshl_add_u64 v[96:97], v[104:105], 1, s[14:15]
	global_load_dwordx4 v[96:99], v[96:97], off
	s_waitcnt vmcnt(0)
	v_lshlrev_b32_e32 v100, 16, v96
	v_and_b32_e32 v101, 0xffff0000, v96
	v_lshlrev_b32_e32 v96, 16, v97
	v_and_b32_e32 v97, 0xffff0000, v97
	v_lshlrev_b32_e32 v102, 16, v98
	v_and_b32_e32 v103, 0xffff0000, v98
	v_lshlrev_b32_e32 v98, 16, v99
	v_and_b32_e32 v99, 0xffff0000, v99
	v_pk_mul_f32 v[92:93], v[92:93], v[100:101]
	v_pk_mul_f32 v[94:95], v[94:95], v[96:97]
	v_pk_mul_f32 v[88:89], v[88:89], v[102:103]
	v_pk_mul_f32 v[90:91], v[90:91], v[98:99]
.LBB0_1104:
	v_lshlrev_b64 v[100:101], 1, v[104:105]
	s_and_b64 vcc, exec, s[0:1]
	v_lshl_add_u64 v[100:101], s[10:11], 0, v[100:101]
	v_or_b32_e32 v104, 0x80, v104
	s_waitcnt vmcnt(0)
	v_pk_mov_b32 v[96:97], v[192:193], v[192:193] op_sel:[0,1] op_sel_hi:[0,1]
	v_pk_mov_b32 v[98:99], v[194:195], v[194:195] op_sel:[0,1] op_sel_hi:[0,1]
	v_lshlrev_b32_e32 v102, 16, v96
	v_and_b32_e32 v103, 0xffff0000, v96
	v_lshlrev_b32_e32 v96, 16, v97
	v_and_b32_e32 v97, 0xffff0000, v97
	v_lshlrev_b32_e32 v106, 16, v98
	v_and_b32_e32 v107, 0xffff0000, v98
	v_lshlrev_b32_e32 v98, 16, v99
	v_and_b32_e32 v99, 0xffff0000, v99
	v_pk_add_f32 v[92:93], v[92:93], v[102:103]
	v_pk_add_f32 v[94:95], v[94:95], v[96:97]
	v_pk_add_f32 v[96:97], v[88:89], v[106:107]
	v_pk_add_f32 v[98:99], v[90:91], v[98:99]
	v_cvt_pk_bf16_f32 v88, v92, v93
	v_cvt_pk_bf16_f32 v89, v94, v95
	v_cvt_pk_bf16_f32 v90, v96, v97
	v_cvt_pk_bf16_f32 v91, v98, v99
	global_store_dwordx4 v[100:101], v[88:91], off
	s_cbranch_vccnz .LBB0_1106
	s_nop 0
	v_lshl_add_u64 v[88:89], v[104:105], 1, s[14:15]
	global_load_dwordx4 v[88:91], v[88:89], off
	s_waitcnt vmcnt(0)
	v_lshlrev_b32_e32 v92, 16, v88
	v_and_b32_e32 v93, 0xffff0000, v88
	v_lshlrev_b32_e32 v88, 16, v89
	v_and_b32_e32 v89, 0xffff0000, v89
	v_lshlrev_b32_e32 v94, 16, v90
	v_and_b32_e32 v95, 0xffff0000, v90
	v_lshlrev_b32_e32 v90, 16, v91
	v_and_b32_e32 v91, 0xffff0000, v91
	v_pk_mul_f32 v[84:85], v[84:85], v[92:93]
	v_pk_mul_f32 v[86:87], v[86:87], v[88:89]
	v_pk_mul_f32 v[80:81], v[80:81], v[94:95]
	v_pk_mul_f32 v[82:83], v[82:83], v[90:91]
.LBB0_1106:
	s_nop 0
	v_lshlrev_b64 v[88:89], 1, v[104:105]
	v_or_b32_e32 v94, 48, v144
	v_ashrrev_i32_e32 v95, 31, v94
	v_lshl_add_u64 v[96:97], s[10:11], 0, v[88:89]
	v_lshlrev_b64 v[88:89], 10, v[94:95]
	s_and_b64 vcc, exec, s[0:1]
	v_or_b32_e32 v88, v88, v162
	s_waitcnt vmcnt(0)
	v_pk_mov_b32 v[90:91], v[196:197], v[196:197] op_sel:[0,1] op_sel_hi:[0,1]
	v_pk_mov_b32 v[92:93], v[198:199], v[198:199] op_sel:[0,1] op_sel_hi:[0,1]
	v_lshlrev_b32_e32 v94, 16, v90
	v_and_b32_e32 v95, 0xffff0000, v90
	v_lshlrev_b32_e32 v90, 16, v91
	v_and_b32_e32 v91, 0xffff0000, v91
	v_lshlrev_b32_e32 v98, 16, v92
	v_and_b32_e32 v99, 0xffff0000, v92
	v_lshlrev_b32_e32 v92, 16, v93
	v_and_b32_e32 v93, 0xffff0000, v93
	v_pk_add_f32 v[84:85], v[84:85], v[94:95]
	v_pk_add_f32 v[86:87], v[86:87], v[90:91]
	v_pk_add_f32 v[90:91], v[80:81], v[98:99]
	v_pk_add_f32 v[92:93], v[82:83], v[92:93]
	v_cvt_pk_bf16_f32 v80, v84, v85
	v_cvt_pk_bf16_f32 v81, v86, v87
	v_cvt_pk_bf16_f32 v82, v90, v91
	v_cvt_pk_bf16_f32 v83, v92, v93
	global_store_dwordx4 v[96:97], v[80:83], off
	s_cbranch_vccnz .LBB0_1108
	s_nop 0
	v_lshl_add_u64 v[80:81], v[88:89], 1, s[14:15]
	global_load_dwordx4 v[80:83], v[80:81], off
	s_waitcnt vmcnt(0)
	v_lshlrev_b32_e32 v84, 16, v80
	v_and_b32_e32 v85, 0xffff0000, v80
	v_lshlrev_b32_e32 v80, 16, v81
	v_and_b32_e32 v81, 0xffff0000, v81
	v_lshlrev_b32_e32 v86, 16, v82
	v_and_b32_e32 v87, 0xffff0000, v82
	v_lshlrev_b32_e32 v82, 16, v83
	v_and_b32_e32 v83, 0xffff0000, v83
	v_pk_mul_f32 v[76:77], v[76:77], v[84:85]
	v_pk_mul_f32 v[78:79], v[78:79], v[80:81]
	v_pk_mul_f32 v[72:73], v[72:73], v[86:87]
	v_pk_mul_f32 v[74:75], v[74:75], v[82:83]
.LBB0_1108:
	v_lshlrev_b64 v[84:85], 1, v[88:89]
	s_and_b64 vcc, exec, s[0:1]
	v_lshl_add_u64 v[84:85], s[10:11], 0, v[84:85]
	v_or_b32_e32 v88, 0x80, v88
	s_waitcnt vmcnt(0)
	v_pk_mov_b32 v[80:81], v[200:201], v[200:201] op_sel:[0,1] op_sel_hi:[0,1]
	v_pk_mov_b32 v[82:83], v[202:203], v[202:203] op_sel:[0,1] op_sel_hi:[0,1]
	v_lshlrev_b32_e32 v86, 16, v80
	v_and_b32_e32 v87, 0xffff0000, v80
	v_lshlrev_b32_e32 v80, 16, v81
	v_and_b32_e32 v81, 0xffff0000, v81
	v_lshlrev_b32_e32 v90, 16, v82
	v_and_b32_e32 v91, 0xffff0000, v82
	v_lshlrev_b32_e32 v82, 16, v83
	v_and_b32_e32 v83, 0xffff0000, v83
	v_pk_add_f32 v[76:77], v[76:77], v[86:87]
	v_pk_add_f32 v[78:79], v[78:79], v[80:81]
	v_pk_add_f32 v[80:81], v[72:73], v[90:91]
	v_pk_add_f32 v[82:83], v[74:75], v[82:83]
	v_cvt_pk_bf16_f32 v72, v76, v77
	v_cvt_pk_bf16_f32 v73, v78, v79
	v_cvt_pk_bf16_f32 v74, v80, v81
	v_cvt_pk_bf16_f32 v75, v82, v83
	global_store_dwordx4 v[84:85], v[72:75], off
	s_cbranch_vccnz .LBB0_1110
	s_nop 0
	v_lshl_add_u64 v[72:73], v[88:89], 1, s[14:15]
	global_load_dwordx4 v[72:75], v[72:73], off
	s_waitcnt vmcnt(0)
	v_lshlrev_b32_e32 v76, 16, v72
	v_and_b32_e32 v77, 0xffff0000, v72
	v_lshlrev_b32_e32 v72, 16, v73
	v_and_b32_e32 v73, 0xffff0000, v73
	v_lshlrev_b32_e32 v78, 16, v74
	v_and_b32_e32 v79, 0xffff0000, v74
	v_lshlrev_b32_e32 v74, 16, v75
	v_and_b32_e32 v75, 0xffff0000, v75
	v_pk_mul_f32 v[68:69], v[68:69], v[76:77]
	v_pk_mul_f32 v[70:71], v[70:71], v[72:73]
	v_pk_mul_f32 v[64:65], v[64:65], v[78:79]
	v_pk_mul_f32 v[66:67], v[66:67], v[74:75]
.LBB0_1110:
	v_lshlrev_b64 v[76:77], 1, v[88:89]
	v_lshlrev_b64 v[78:79], 10, v[144:145]
	v_lshl_add_u64 v[76:77], s[10:11], 0, v[76:77]
	v_or_b32_e32 v78, v78, v162
	s_and_b64 vcc, exec, s[0:1]
	s_waitcnt vmcnt(0)
	v_pk_mov_b32 v[72:73], v[204:205], v[204:205] op_sel:[0,1] op_sel_hi:[0,1]
	v_pk_mov_b32 v[74:75], v[206:207], v[206:207] op_sel:[0,1] op_sel_hi:[0,1]
	v_lshlrev_b32_e32 v80, 16, v72
	v_and_b32_e32 v81, 0xffff0000, v72
	v_lshlrev_b32_e32 v72, 16, v73
	v_and_b32_e32 v73, 0xffff0000, v73
	v_lshlrev_b32_e32 v82, 16, v74
	v_and_b32_e32 v83, 0xffff0000, v74
	v_lshlrev_b32_e32 v74, 16, v75
	v_and_b32_e32 v75, 0xffff0000, v75
	v_pk_add_f32 v[68:69], v[68:69], v[80:81]
	v_pk_add_f32 v[70:71], v[70:71], v[72:73]
	v_pk_add_f32 v[72:73], v[64:65], v[82:83]
	v_pk_add_f32 v[74:75], v[66:67], v[74:75]
	v_cvt_pk_bf16_f32 v64, v68, v69
	v_cvt_pk_bf16_f32 v65, v70, v71
	v_cvt_pk_bf16_f32 v66, v72, v73
	v_cvt_pk_bf16_f32 v67, v74, v75
	global_store_dwordx4 v[76:77], v[64:67], off
	s_nop 1
	v_lshl_add_u64 v[64:65], v[78:79], 0, s[22:23]
	s_cbranch_vccnz .LBB0_1112
	v_lshl_add_u64 v[66:67], v[64:65], 1, s[14:15]
	global_load_dwordx4 v[66:69], v[66:67], off
	s_waitcnt vmcnt(0)
	v_lshlrev_b32_e32 v70, 16, v66
	v_and_b32_e32 v71, 0xffff0000, v66
	v_lshlrev_b32_e32 v66, 16, v67
	v_and_b32_e32 v67, 0xffff0000, v67
	v_lshlrev_b32_e32 v72, 16, v68
	v_and_b32_e32 v73, 0xffff0000, v68
	v_lshlrev_b32_e32 v68, 16, v69
	v_and_b32_e32 v69, 0xffff0000, v69
	v_pk_mul_f32 v[60:61], v[60:61], v[70:71]
	v_pk_mul_f32 v[62:63], v[62:63], v[66:67]
	v_pk_mul_f32 v[56:57], v[56:57], v[72:73]
	v_pk_mul_f32 v[58:59], v[58:59], v[68:69]
.LBB0_1112:
	v_lshlrev_b64 v[70:71], 1, v[64:65]
	s_and_b64 vcc, exec, s[0:1]
	v_lshl_add_u64 v[70:71], s[10:11], 0, v[70:71]
	v_or_b32_e32 v64, 0x80, v64
	s_waitcnt vmcnt(0)
	v_pk_mov_b32 v[66:67], v[208:209], v[208:209] op_sel:[0,1] op_sel_hi:[0,1]
	v_pk_mov_b32 v[68:69], v[210:211], v[210:211] op_sel:[0,1] op_sel_hi:[0,1]
	v_lshlrev_b32_e32 v72, 16, v66
	v_and_b32_e32 v73, 0xffff0000, v66
	v_lshlrev_b32_e32 v66, 16, v67
	v_and_b32_e32 v67, 0xffff0000, v67
	v_lshlrev_b32_e32 v74, 16, v68
	v_and_b32_e32 v75, 0xffff0000, v68
	v_lshlrev_b32_e32 v68, 16, v69
	v_and_b32_e32 v69, 0xffff0000, v69
	v_pk_add_f32 v[60:61], v[60:61], v[72:73]
	v_pk_add_f32 v[62:63], v[62:63], v[66:67]
	v_pk_add_f32 v[66:67], v[56:57], v[74:75]
	v_pk_add_f32 v[68:69], v[58:59], v[68:69]
	v_cvt_pk_bf16_f32 v56, v60, v61
	v_cvt_pk_bf16_f32 v57, v62, v63
	v_cvt_pk_bf16_f32 v58, v66, v67
	v_cvt_pk_bf16_f32 v59, v68, v69
	global_store_dwordx4 v[70:71], v[56:59], off
	s_cbranch_vccnz .LBB0_1114
	s_nop 0
	v_lshl_add_u64 v[56:57], v[64:65], 1, s[14:15]
	global_load_dwordx4 v[56:59], v[56:57], off
	s_waitcnt vmcnt(0)
	v_lshlrev_b32_e32 v60, 16, v56
	v_and_b32_e32 v61, 0xffff0000, v56
	v_lshlrev_b32_e32 v56, 16, v57
	v_and_b32_e32 v57, 0xffff0000, v57
	v_lshlrev_b32_e32 v62, 16, v58
	v_and_b32_e32 v63, 0xffff0000, v58
	v_lshlrev_b32_e32 v58, 16, v59
	v_and_b32_e32 v59, 0xffff0000, v59
	v_pk_mul_f32 v[52:53], v[52:53], v[60:61]
	v_pk_mul_f32 v[54:55], v[54:55], v[56:57]
	v_pk_mul_f32 v[48:49], v[48:49], v[62:63]
	v_pk_mul_f32 v[50:51], v[50:51], v[58:59]
.LBB0_1114:
	v_lshlrev_b64 v[60:61], 1, v[64:65]
	v_lshlrev_b64 v[62:63], 10, v[144:145]
	v_lshl_add_u64 v[60:61], s[10:11], 0, v[60:61]
	v_or_b32_e32 v62, v62, v162
	s_and_b64 vcc, exec, s[0:1]
	s_waitcnt vmcnt(0)
	v_pk_mov_b32 v[56:57], v[212:213], v[212:213] op_sel:[0,1] op_sel_hi:[0,1]
	v_pk_mov_b32 v[58:59], v[214:215], v[214:215] op_sel:[0,1] op_sel_hi:[0,1]
	v_lshlrev_b32_e32 v64, 16, v56
	v_and_b32_e32 v65, 0xffff0000, v56
	v_lshlrev_b32_e32 v56, 16, v57
	v_and_b32_e32 v57, 0xffff0000, v57
	v_lshlrev_b32_e32 v66, 16, v58
	v_and_b32_e32 v67, 0xffff0000, v58
	v_lshlrev_b32_e32 v58, 16, v59
	v_and_b32_e32 v59, 0xffff0000, v59
	v_pk_add_f32 v[52:53], v[52:53], v[64:65]
	v_pk_add_f32 v[54:55], v[54:55], v[56:57]
	v_pk_add_f32 v[56:57], v[48:49], v[66:67]
	v_pk_add_f32 v[58:59], v[50:51], v[58:59]
	v_cvt_pk_bf16_f32 v48, v52, v53
	v_cvt_pk_bf16_f32 v49, v54, v55
	v_cvt_pk_bf16_f32 v50, v56, v57
	v_cvt_pk_bf16_f32 v51, v58, v59
	global_store_dwordx4 v[60:61], v[48:51], off
	s_nop 1
	v_lshl_add_u64 v[48:49], v[62:63], 0, s[24:25]
	s_cbranch_vccnz .LBB0_1116
	v_lshl_add_u64 v[50:51], v[48:49], 1, s[14:15]
	global_load_dwordx4 v[50:53], v[50:51], off
	s_waitcnt vmcnt(0)
	v_lshlrev_b32_e32 v54, 16, v50
	v_and_b32_e32 v55, 0xffff0000, v50
	v_lshlrev_b32_e32 v50, 16, v51
	v_and_b32_e32 v51, 0xffff0000, v51
	v_lshlrev_b32_e32 v56, 16, v52
	v_and_b32_e32 v57, 0xffff0000, v52
	v_lshlrev_b32_e32 v52, 16, v53
	v_and_b32_e32 v53, 0xffff0000, v53
	v_pk_mul_f32 v[44:45], v[44:45], v[54:55]
	v_pk_mul_f32 v[46:47], v[46:47], v[50:51]
	v_pk_mul_f32 v[40:41], v[40:41], v[56:57]
	v_pk_mul_f32 v[42:43], v[42:43], v[52:53]
.LBB0_1116:
	v_lshlrev_b64 v[54:55], 1, v[48:49]
	s_and_b64 vcc, exec, s[0:1]
	v_lshl_add_u64 v[54:55], s[10:11], 0, v[54:55]
	v_or_b32_e32 v48, 0x80, v48
	s_waitcnt vmcnt(0)
	v_pk_mov_b32 v[50:51], v[216:217], v[216:217] op_sel:[0,1] op_sel_hi:[0,1]
	v_pk_mov_b32 v[52:53], v[218:219], v[218:219] op_sel:[0,1] op_sel_hi:[0,1]
	v_lshlrev_b32_e32 v56, 16, v50
	v_and_b32_e32 v57, 0xffff0000, v50
	v_lshlrev_b32_e32 v50, 16, v51
	v_and_b32_e32 v51, 0xffff0000, v51
	v_lshlrev_b32_e32 v58, 16, v52
	v_and_b32_e32 v59, 0xffff0000, v52
	v_lshlrev_b32_e32 v52, 16, v53
	v_and_b32_e32 v53, 0xffff0000, v53
	v_pk_add_f32 v[44:45], v[44:45], v[56:57]
	v_pk_add_f32 v[46:47], v[46:47], v[50:51]
	v_pk_add_f32 v[50:51], v[40:41], v[58:59]
	v_pk_add_f32 v[52:53], v[42:43], v[52:53]
	v_cvt_pk_bf16_f32 v40, v44, v45
	v_cvt_pk_bf16_f32 v41, v46, v47
	v_cvt_pk_bf16_f32 v42, v50, v51
	v_cvt_pk_bf16_f32 v43, v52, v53
	global_store_dwordx4 v[54:55], v[40:43], off
	s_cbranch_vccnz .LBB0_1118
	s_nop 0
	v_lshl_add_u64 v[40:41], v[48:49], 1, s[14:15]
	global_load_dwordx4 v[40:43], v[40:41], off
	s_waitcnt vmcnt(0)
	v_lshlrev_b32_e32 v44, 16, v40
	v_and_b32_e32 v45, 0xffff0000, v40
	v_lshlrev_b32_e32 v40, 16, v41
	v_and_b32_e32 v41, 0xffff0000, v41
	v_lshlrev_b32_e32 v46, 16, v42
	v_and_b32_e32 v47, 0xffff0000, v42
	v_lshlrev_b32_e32 v42, 16, v43
	v_and_b32_e32 v43, 0xffff0000, v43
	v_pk_mul_f32 v[36:37], v[36:37], v[44:45]
	v_pk_mul_f32 v[38:39], v[38:39], v[40:41]
	v_pk_mul_f32 v[32:33], v[32:33], v[46:47]
	v_pk_mul_f32 v[34:35], v[34:35], v[42:43]
.LBB0_1118:
	v_lshlrev_b64 v[44:45], 1, v[48:49]
	v_lshlrev_b64 v[46:47], 10, v[144:145]
	v_lshl_add_u64 v[44:45], s[10:11], 0, v[44:45]
	v_or_b32_e32 v46, v46, v162
	s_and_b64 vcc, exec, s[0:1]
	s_waitcnt vmcnt(0)
	v_pk_mov_b32 v[40:41], v[220:221], v[220:221] op_sel:[0,1] op_sel_hi:[0,1]
	v_pk_mov_b32 v[42:43], v[222:223], v[222:223] op_sel:[0,1] op_sel_hi:[0,1]
	v_lshlrev_b32_e32 v48, 16, v40
	v_and_b32_e32 v49, 0xffff0000, v40
	v_lshlrev_b32_e32 v40, 16, v41
	v_and_b32_e32 v41, 0xffff0000, v41
	v_lshlrev_b32_e32 v50, 16, v42
	v_and_b32_e32 v51, 0xffff0000, v42
	v_lshlrev_b32_e32 v42, 16, v43
	v_and_b32_e32 v43, 0xffff0000, v43
	v_pk_add_f32 v[36:37], v[36:37], v[48:49]
	v_pk_add_f32 v[38:39], v[38:39], v[40:41]
	v_pk_add_f32 v[40:41], v[32:33], v[50:51]
	v_pk_add_f32 v[42:43], v[34:35], v[42:43]
	v_cvt_pk_bf16_f32 v32, v36, v37
	v_cvt_pk_bf16_f32 v33, v38, v39
	v_cvt_pk_bf16_f32 v34, v40, v41
	v_cvt_pk_bf16_f32 v35, v42, v43
	global_store_dwordx4 v[44:45], v[32:35], off
	s_nop 1
	v_lshl_add_u64 v[32:33], v[46:47], 0, s[26:27]
	s_cbranch_vccnz .LBB0_1120
	v_lshl_add_u64 v[34:35], v[32:33], 1, s[14:15]
	global_load_dwordx4 v[34:37], v[34:35], off
	s_waitcnt vmcnt(0)
	v_lshlrev_b32_e32 v38, 16, v34
	v_and_b32_e32 v39, 0xffff0000, v34
	v_lshlrev_b32_e32 v34, 16, v35
	v_and_b32_e32 v35, 0xffff0000, v35
	v_lshlrev_b32_e32 v40, 16, v36
	v_and_b32_e32 v41, 0xffff0000, v36
	v_lshlrev_b32_e32 v36, 16, v37
	v_and_b32_e32 v37, 0xffff0000, v37
	v_pk_mul_f32 v[28:29], v[28:29], v[38:39]
	v_pk_mul_f32 v[30:31], v[30:31], v[34:35]
	v_pk_mul_f32 v[24:25], v[24:25], v[40:41]
	v_pk_mul_f32 v[26:27], v[26:27], v[36:37]
.LBB0_1120:
	v_lshlrev_b64 v[38:39], 1, v[32:33]
	s_and_b64 vcc, exec, s[0:1]
	v_lshl_add_u64 v[38:39], s[10:11], 0, v[38:39]
	v_or_b32_e32 v32, 0x80, v32
	s_waitcnt vmcnt(0)
	v_pk_mov_b32 v[34:35], v[224:225], v[224:225] op_sel:[0,1] op_sel_hi:[0,1]
	v_pk_mov_b32 v[36:37], v[226:227], v[226:227] op_sel:[0,1] op_sel_hi:[0,1]
	v_lshlrev_b32_e32 v40, 16, v34
	v_and_b32_e32 v41, 0xffff0000, v34
	v_lshlrev_b32_e32 v34, 16, v35
	v_and_b32_e32 v35, 0xffff0000, v35
	v_lshlrev_b32_e32 v42, 16, v36
	v_and_b32_e32 v43, 0xffff0000, v36
	v_lshlrev_b32_e32 v36, 16, v37
	v_and_b32_e32 v37, 0xffff0000, v37
	v_pk_add_f32 v[28:29], v[28:29], v[40:41]
	v_pk_add_f32 v[30:31], v[30:31], v[34:35]
	v_pk_add_f32 v[34:35], v[24:25], v[42:43]
	v_pk_add_f32 v[36:37], v[26:27], v[36:37]
	v_cvt_pk_bf16_f32 v24, v28, v29
	v_cvt_pk_bf16_f32 v25, v30, v31
	v_cvt_pk_bf16_f32 v26, v34, v35
	v_cvt_pk_bf16_f32 v27, v36, v37
	global_store_dwordx4 v[38:39], v[24:27], off
	s_cbranch_vccnz .LBB0_1122
	s_nop 0
	v_lshl_add_u64 v[24:25], v[32:33], 1, s[14:15]
	global_load_dwordx4 v[24:27], v[24:25], off
	s_waitcnt vmcnt(0)
	v_lshlrev_b32_e32 v28, 16, v24
	v_and_b32_e32 v29, 0xffff0000, v24
	v_lshlrev_b32_e32 v24, 16, v25
	v_and_b32_e32 v25, 0xffff0000, v25
	v_lshlrev_b32_e32 v30, 16, v26
	v_and_b32_e32 v31, 0xffff0000, v26
	v_lshlrev_b32_e32 v26, 16, v27
	v_and_b32_e32 v27, 0xffff0000, v27
	v_pk_mul_f32 v[20:21], v[20:21], v[28:29]
	v_pk_mul_f32 v[22:23], v[22:23], v[24:25]
	v_pk_mul_f32 v[16:17], v[16:17], v[30:31]
	v_pk_mul_f32 v[18:19], v[18:19], v[26:27]
.LBB0_1122:
	v_lshlrev_b64 v[28:29], 1, v[32:33]
	v_lshlrev_b64 v[30:31], 10, v[144:145]
	v_lshl_add_u64 v[28:29], s[10:11], 0, v[28:29]
	v_or_b32_e32 v30, v30, v162
	s_and_b64 vcc, exec, s[0:1]
	s_waitcnt vmcnt(0)
	v_pk_mov_b32 v[24:25], v[228:229], v[228:229] op_sel:[0,1] op_sel_hi:[0,1]
	v_pk_mov_b32 v[26:27], v[230:231], v[230:231] op_sel:[0,1] op_sel_hi:[0,1]
	v_lshlrev_b32_e32 v32, 16, v24
	v_and_b32_e32 v33, 0xffff0000, v24
	v_lshlrev_b32_e32 v24, 16, v25
	v_and_b32_e32 v25, 0xffff0000, v25
	v_lshlrev_b32_e32 v34, 16, v26
	v_and_b32_e32 v35, 0xffff0000, v26
	v_lshlrev_b32_e32 v26, 16, v27
	v_and_b32_e32 v27, 0xffff0000, v27
	v_pk_add_f32 v[20:21], v[20:21], v[32:33]
	v_pk_add_f32 v[22:23], v[22:23], v[24:25]
	v_pk_add_f32 v[24:25], v[16:17], v[34:35]
	v_pk_add_f32 v[26:27], v[18:19], v[26:27]
	v_cvt_pk_bf16_f32 v16, v20, v21
	v_cvt_pk_bf16_f32 v17, v22, v23
	v_cvt_pk_bf16_f32 v18, v24, v25
	v_cvt_pk_bf16_f32 v19, v26, v27
	global_store_dwordx4 v[28:29], v[16:19], off
	s_nop 1
	v_lshl_add_u64 v[16:17], v[30:31], 0, s[34:35]
	s_cbranch_vccnz .LBB0_1124
	v_lshl_add_u64 v[18:19], v[16:17], 1, s[14:15]
	global_load_dwordx4 v[18:21], v[18:19], off
	s_waitcnt vmcnt(0)
	v_lshlrev_b32_e32 v22, 16, v18
	v_and_b32_e32 v23, 0xffff0000, v18
	v_lshlrev_b32_e32 v18, 16, v19
	v_and_b32_e32 v19, 0xffff0000, v19
	v_lshlrev_b32_e32 v24, 16, v20
	v_and_b32_e32 v25, 0xffff0000, v20
	v_lshlrev_b32_e32 v20, 16, v21
	v_and_b32_e32 v21, 0xffff0000, v21
	v_pk_mul_f32 v[12:13], v[12:13], v[22:23]
	v_pk_mul_f32 v[14:15], v[14:15], v[18:19]
	v_pk_mul_f32 v[8:9], v[8:9], v[24:25]
	v_pk_mul_f32 v[10:11], v[10:11], v[20:21]
.LBB0_1124:
	v_lshlrev_b64 v[22:23], 1, v[16:17]
	s_cmp_gt_u32 s20, 3
	v_lshl_add_u64 v[22:23], s[10:11], 0, v[22:23]
	v_or_b32_e32 v16, 0x80, v16
	s_waitcnt vmcnt(0)
	v_pk_mov_b32 v[18:19], v[232:233], v[232:233] op_sel:[0,1] op_sel_hi:[0,1]
	v_pk_mov_b32 v[20:21], v[234:235], v[234:235] op_sel:[0,1] op_sel_hi:[0,1]
	v_lshlrev_b32_e32 v24, 16, v18
	v_and_b32_e32 v25, 0xffff0000, v18
	v_lshlrev_b32_e32 v18, 16, v19
	v_and_b32_e32 v19, 0xffff0000, v19
	v_lshlrev_b32_e32 v26, 16, v20
	v_and_b32_e32 v27, 0xffff0000, v20
	v_lshlrev_b32_e32 v20, 16, v21
	v_and_b32_e32 v21, 0xffff0000, v21
	v_pk_add_f32 v[12:13], v[12:13], v[24:25]
	v_pk_add_f32 v[14:15], v[14:15], v[18:19]
	v_pk_add_f32 v[18:19], v[8:9], v[26:27]
	v_pk_add_f32 v[20:21], v[10:11], v[20:21]
	v_cvt_pk_bf16_f32 v8, v12, v13
	v_cvt_pk_bf16_f32 v9, v14, v15
	v_cvt_pk_bf16_f32 v10, v18, v19
	v_cvt_pk_bf16_f32 v11, v20, v21
	global_store_dwordx4 v[22:23], v[8:11], off
	s_cbranch_scc1 .LBB0_1126
	s_nop 0
	v_lshl_add_u64 v[8:9], v[16:17], 1, s[14:15]
	global_load_dwordx4 v[8:11], v[8:9], off
	s_waitcnt vmcnt(0)
	v_lshlrev_b32_e32 v12, 16, v8
	v_and_b32_e32 v13, 0xffff0000, v8
	v_lshlrev_b32_e32 v8, 16, v9
	v_and_b32_e32 v9, 0xffff0000, v9
	v_lshlrev_b32_e32 v14, 16, v10
	v_and_b32_e32 v15, 0xffff0000, v10
	v_lshlrev_b32_e32 v10, 16, v11
	v_and_b32_e32 v11, 0xffff0000, v11
	v_pk_mul_f32 v[4:5], v[4:5], v[12:13]
	v_pk_mul_f32 v[6:7], v[6:7], v[8:9]
	v_pk_mul_f32 v[0:1], v[0:1], v[14:15]
	v_pk_mul_f32 v[2:3], v[2:3], v[10:11]
.LBB0_1126:
	v_lshlrev_b64 v[12:13], 1, v[16:17]
	v_lshl_add_u64 v[12:13], s[10:11], 0, v[12:13]
	s_andn2_b64 vcc, exec, s[6:7]
	s_mov_b64 s[0:1], -1
	s_waitcnt vmcnt(0)
	v_pk_mov_b32 v[8:9], v[236:237], v[236:237] op_sel:[0,1] op_sel_hi:[0,1]
	v_pk_mov_b32 v[10:11], v[238:239], v[238:239] op_sel:[0,1] op_sel_hi:[0,1]
	v_lshlrev_b32_e32 v14, 16, v8
	v_and_b32_e32 v15, 0xffff0000, v8
	v_lshlrev_b32_e32 v8, 16, v9
	v_and_b32_e32 v9, 0xffff0000, v9
	v_lshlrev_b32_e32 v16, 16, v10
	v_and_b32_e32 v17, 0xffff0000, v10
	v_lshlrev_b32_e32 v10, 16, v11
	v_and_b32_e32 v11, 0xffff0000, v11
	v_pk_add_f32 v[4:5], v[4:5], v[14:15]
	v_pk_add_f32 v[6:7], v[6:7], v[8:9]
	v_pk_add_f32 v[8:9], v[0:1], v[16:17]
	v_pk_add_f32 v[10:11], v[2:3], v[10:11]
	v_cvt_pk_bf16_f32 v0, v4, v5
	v_cvt_pk_bf16_f32 v1, v6, v7
	v_cvt_pk_bf16_f32 v2, v8, v9
	v_cvt_pk_bf16_f32 v3, v10, v11
	global_store_dwordx4 v[12:13], v[0:3], off
	s_cbranch_vccnz .LBB0_1083
	s_andn2_b64 vcc, exec, s[12:13]
	s_cbranch_vccnz .LBB0_1082
	s_barrier
	s_branch .LBB0_1082
